# grid barrier release one hop shorter: follower workgroups poll the global generation word directly instead of the per-XCD one
# speedup vs baseline: 1.0096x; 1.0038x over previous
.Lxb1_follow:
	v_readlane_b32 s100, v254, 14
	v_readlane_b32 s101, v254, 15
	s_nop 1
	v_mov_b32_e32 v8, s100
	v_mov_b32_e32 v9, s101
